# peeled first half-iteration of both GEMM K-loops with C=0 MFMAs (no accumulator zeroing)
# baseline (speedup 1.0000x reference)
.LBB0_409:
	s_andn2_b64 vcc, exec, s[76:77]
	s_cbranch_vccnz .Lzs_B
	s_add_u32 s42, s84, 0x80
	s_addc_u32 s43, s85, 0
	s_add_u32 s48, s44, 0x100
	s_addc_u32 s49, s45, 0
	s_mov_b32 s44, 0
	s_add_i32 s84, s44, 2
	s_add_u32 s10, s42, 0x80
	s_addc_u32 s45, s43, 0
	s_add_i32 s52, 0, 0x10000
	s_cmp_eq_u32 s30, s44
	s_cselect_b32 s45, s81, s45
	s_cselect_b32 s44, s80, s10
	v_add_u32_e32 v32, s52, v216
	s_cselect_b32 s91, s83, s49
	s_cselect_b32 s90, s82, s48
	s_add_i32 s10, 0, 0x14000
	ds_read_b128 v[74:77], v32
	ds_read_b128 v[78:81], v32 offset:1024
	ds_read_b128 v[90:93], v32 offset:2048
	ds_read_b128 v[94:97], v32 offset:3072
	v_add_u32_e32 v32, s10, v216
	ds_read_b128 v[98:101], v32
	ds_read_b128 v[102:105], v32 offset:1024
	ds_read_b128 v[106:109], v32 offset:2048
	ds_read_b128 v[110:113], v32 offset:3072
	v_lshl_add_u64 v[188:189], s[42:43], 0, v[176:177]
	s_add_i32 m0, s3, 0xc000
	ds_read_b128 v[162:165], v218
	ds_read_b128 v[180:183], v218 offset:1024
	ds_read_b128 v[184:187], v218 offset:2048
	ds_read_b128 v[224:227], v218 offset:3072
	ds_read_b128 v[228:231], v218 offset:4096
	ds_read_b128 v[232:235], v218 offset:5120
	ds_read_b128 v[236:239], v218 offset:6144
	ds_read_b128 v[240:243], v218 offset:7168
	global_load_lds_dwordx4 v[188:189], off
	v_lshl_add_u64 v[188:189], s[42:43], 0, v[178:179]
	s_add_i32 m0, s3, 0xe000
	s_nop 0
	global_load_lds_dwordx4 v[188:189], off
	s_waitcnt vmcnt(8)
	s_waitcnt lgkmcnt(0)
	s_barrier
	s_setprio 1
	s_waitcnt lgkmcnt(0)
	s_nop 0
	v_mfma_f32_16x16x32_bf16 v[154:157], v[74:77], v[162:165], 0
	v_mfma_f32_16x16x32_bf16 v[158:161], v[90:93], v[162:165], 0
	v_mfma_f32_16x16x32_bf16 v[142:145], v[74:77], v[184:187], 0
	v_mfma_f32_16x16x32_bf16 v[138:141], v[90:93], v[184:187], 0
	v_mfma_f32_16x16x32_bf16 v[126:129], v[74:77], v[228:231], 0
	v_mfma_f32_16x16x32_bf16 v[122:125], v[90:93], v[228:231], 0
	v_mfma_f32_16x16x32_bf16 v[86:89], v[74:77], v[236:239], 0
	v_mfma_f32_16x16x32_bf16 v[82:85], v[90:93], v[236:239], 0
	v_mfma_f32_16x16x32_bf16 v[154:157], v[78:81], v[180:183], v[154:157]
	v_mfma_f32_16x16x32_bf16 v[158:161], v[94:97], v[180:183], v[158:161]
	v_mfma_f32_16x16x32_bf16 v[142:145], v[78:81], v[224:227], v[142:145]
	v_mfma_f32_16x16x32_bf16 v[138:141], v[94:97], v[224:227], v[138:141]
	v_mfma_f32_16x16x32_bf16 v[126:129], v[78:81], v[232:235], v[126:129]
	v_mfma_f32_16x16x32_bf16 v[122:125], v[94:97], v[232:235], v[122:125]
	v_mfma_f32_16x16x32_bf16 v[86:89], v[78:81], v[240:243], v[86:89]
	v_mfma_f32_16x16x32_bf16 v[82:85], v[94:97], v[240:243], v[82:85]
	s_setprio 0
	s_setprio 1
	v_mfma_f32_16x16x32_bf16 v[150:153], v[98:101], v[162:165], 0
	v_mfma_f32_16x16x32_bf16 v[146:149], v[106:109], v[162:165], 0
	v_mfma_f32_16x16x32_bf16 v[134:137], v[98:101], v[184:187], 0
	v_mfma_f32_16x16x32_bf16 v[130:133], v[106:109], v[184:187], 0
	v_mfma_f32_16x16x32_bf16 v[118:121], v[98:101], v[228:231], 0
	v_mfma_f32_16x16x32_bf16 v[114:117], v[106:109], v[228:231], 0
	v_mfma_f32_16x16x32_bf16 v[70:73], v[98:101], v[236:239], 0
	v_mfma_f32_16x16x32_bf16 v[66:69], v[106:109], v[236:239], 0
	v_mfma_f32_16x16x32_bf16 v[150:153], v[102:105], v[180:183], v[150:153]
	v_mfma_f32_16x16x32_bf16 v[146:149], v[110:113], v[180:183], v[146:149]
	v_mfma_f32_16x16x32_bf16 v[134:137], v[102:105], v[224:227], v[134:137]
	v_mfma_f32_16x16x32_bf16 v[130:133], v[110:113], v[224:227], v[130:133]
	v_mfma_f32_16x16x32_bf16 v[118:121], v[102:105], v[232:235], v[118:121]
	v_mfma_f32_16x16x32_bf16 v[114:117], v[110:113], v[232:235], v[114:117]
	v_mfma_f32_16x16x32_bf16 v[70:73], v[102:105], v[240:243], v[70:73]
	v_mfma_f32_16x16x32_bf16 v[66:69], v[110:113], v[240:243], v[66:69]
	s_setprio 0
	s_barrier
	s_add_i32 s52, s52, s2
	v_lshl_add_u64 v[188:189], s[90:91], 0, v[170:171]
	s_mov_b32 m0, s52
	s_bitcmp1_b32 s99, 0
	s_cbranch_scc1 .LhpB_r0
	ds_read_b128 v[162:165], v218 offset:16384
	ds_read_b128 v[180:183], v218 offset:17408
	ds_read_b128 v[184:187], v218 offset:18432
	ds_read_b128 v[224:227], v218 offset:19456
	ds_read_b128 v[228:231], v218 offset:20480
	ds_read_b128 v[232:235], v218 offset:21504
	ds_read_b128 v[236:239], v218 offset:22528
	ds_read_b128 v[240:243], v218 offset:23552
.LhpB_r0:
	global_load_lds_dwordx4 v[188:189], off
	s_add_i32 m0, s52, 0x2000
	v_lshl_add_u64 v[202:203], s[90:91], 0, v[174:175]
	s_add_u32 s90, s90, s0
	s_addc_u32 s91, s91, s1
	s_add_i32 s10, s10, s2
	global_load_lds_dwordx4 v[202:203], off
	v_lshl_add_u64 v[204:205], s[90:91], 0, v[170:171]
	s_mov_b32 m0, s10
	v_lshl_add_u64 v[212:213], s[90:91], 0, v[174:175]
	global_load_lds_dwordx4 v[204:205], off
	s_add_i32 m0, s10, 0x2000
	v_lshl_add_u64 v[244:245], s[44:45], 0, v[168:169]
	global_load_lds_dwordx4 v[212:213], off
	s_mov_b32 m0, s3
	v_lshl_add_u64 v[246:247], s[44:45], 0, v[172:173]
	global_load_lds_dwordx4 v[244:245], off
	s_mov_b32 m0, s7
	s_nop 0
	global_load_lds_dwordx4 v[246:247], off
	s_waitcnt vmcnt(8)
	s_waitcnt lgkmcnt(0)
	s_barrier
	s_setprio 1
	s_waitcnt lgkmcnt(0)
	s_bitcmp1_b32 s99, 0
	s_cbranch_scc1 .LhpB_m1
	v_mfma_f32_16x16x32_bf16 v[62:65], v[74:77], v[162:165], 0
	v_mfma_f32_16x16x32_bf16 v[58:61], v[90:93], v[162:165], 0
	v_mfma_f32_16x16x32_bf16 v[46:49], v[74:77], v[184:187], 0
	v_mfma_f32_16x16x32_bf16 v[42:45], v[90:93], v[184:187], 0
	v_mfma_f32_16x16x32_bf16 v[28:31], v[74:77], v[228:231], 0
	v_mfma_f32_16x16x32_bf16 v[24:27], v[90:93], v[228:231], 0
	v_mfma_f32_16x16x32_bf16 v[12:15], v[74:77], v[236:239], 0
	v_mfma_f32_16x16x32_bf16 v[8:11], v[90:93], v[236:239], 0
	v_mfma_f32_16x16x32_bf16 v[62:65], v[78:81], v[180:183], v[62:65]
	v_mfma_f32_16x16x32_bf16 v[58:61], v[94:97], v[180:183], v[58:61]
	v_mfma_f32_16x16x32_bf16 v[46:49], v[78:81], v[224:227], v[46:49]
	v_mfma_f32_16x16x32_bf16 v[42:45], v[94:97], v[224:227], v[42:45]
	v_mfma_f32_16x16x32_bf16 v[28:31], v[78:81], v[232:235], v[28:31]
	v_mfma_f32_16x16x32_bf16 v[24:27], v[94:97], v[232:235], v[24:27]
	v_mfma_f32_16x16x32_bf16 v[12:15], v[78:81], v[240:243], v[12:15]
	v_mfma_f32_16x16x32_bf16 v[8:11], v[94:97], v[240:243], v[8:11]
	s_setprio 0
	s_setprio 1
	v_mfma_f32_16x16x32_bf16 v[54:57], v[98:101], v[162:165], 0
	v_mfma_f32_16x16x32_bf16 v[50:53], v[106:109], v[162:165], 0
	v_mfma_f32_16x16x32_bf16 v[38:41], v[98:101], v[184:187], 0
	v_mfma_f32_16x16x32_bf16 v[34:37], v[106:109], v[184:187], 0
	v_mfma_f32_16x16x32_bf16 v[20:23], v[98:101], v[228:231], 0
	v_mfma_f32_16x16x32_bf16 v[16:19], v[106:109], v[228:231], 0
	v_mfma_f32_16x16x32_bf16 v[4:7], v[98:101], v[236:239], 0
	v_mfma_f32_16x16x32_bf16 v[0:3], v[106:109], v[236:239], 0
	v_mfma_f32_16x16x32_bf16 v[54:57], v[102:105], v[180:183], v[54:57]
	v_mfma_f32_16x16x32_bf16 v[50:53], v[110:113], v[180:183], v[50:53]
	v_mfma_f32_16x16x32_bf16 v[38:41], v[102:105], v[224:227], v[38:41]
	v_mfma_f32_16x16x32_bf16 v[34:37], v[110:113], v[224:227], v[34:37]
	v_mfma_f32_16x16x32_bf16 v[20:23], v[102:105], v[232:235], v[20:23]
	v_mfma_f32_16x16x32_bf16 v[16:19], v[110:113], v[232:235], v[16:19]
	v_mfma_f32_16x16x32_bf16 v[4:7], v[102:105], v[240:243], v[4:7]
	v_mfma_f32_16x16x32_bf16 v[0:3], v[110:113], v[240:243], v[0:3]
.LhpB_m1:
	s_setprio 0
	s_barrier
	s_branch .Ljoin_B
.Lzs_B:
	v_mov_b32_e32 v157, 0
	v_mov_b32_e32 v156, v157
	v_mov_b32_e32 v155, v157
	v_mov_b32_e32 v154, v157
	v_mov_b32_e32 v161, v157
	v_mov_b32_e32 v160, v157
	v_mov_b32_e32 v159, v157
	v_mov_b32_e32 v158, v157
	v_mov_b32_e32 v145, v157
	v_mov_b32_e32 v144, v157
	v_mov_b32_e32 v143, v157
	v_mov_b32_e32 v142, v157
	v_mov_b32_e32 v141, v157
	v_mov_b32_e32 v140, v157
	v_mov_b32_e32 v139, v157
	v_mov_b32_e32 v138, v157
	v_mov_b32_e32 v129, v157
	v_mov_b32_e32 v128, v157
	v_mov_b32_e32 v127, v157
	v_mov_b32_e32 v126, v157
	v_mov_b32_e32 v125, v157
	v_mov_b32_e32 v124, v157
	v_mov_b32_e32 v123, v157
	v_mov_b32_e32 v122, v157
	v_mov_b32_e32 v89, v157
	v_mov_b32_e32 v88, v157
	v_mov_b32_e32 v87, v157
	v_mov_b32_e32 v86, v157
	v_mov_b32_e32 v85, v157
	v_mov_b32_e32 v84, v157
	v_mov_b32_e32 v83, v157
	v_mov_b32_e32 v82, v157
	v_mov_b32_e32 v153, v157
	v_mov_b32_e32 v152, v157
	v_mov_b32_e32 v151, v157
	v_mov_b32_e32 v150, v157
	v_mov_b32_e32 v149, v157
	v_mov_b32_e32 v148, v157
	v_mov_b32_e32 v147, v157
	v_mov_b32_e32 v146, v157
	v_mov_b32_e32 v137, v157
	v_mov_b32_e32 v136, v157
	v_mov_b32_e32 v135, v157
	v_mov_b32_e32 v134, v157
	v_mov_b32_e32 v133, v157
	v_mov_b32_e32 v132, v157
	v_mov_b32_e32 v131, v157
	v_mov_b32_e32 v130, v157
	v_mov_b32_e32 v121, v157
	v_mov_b32_e32 v120, v157
	v_mov_b32_e32 v119, v157
	v_mov_b32_e32 v118, v157
	v_mov_b32_e32 v117, v157
	v_mov_b32_e32 v116, v157
	v_mov_b32_e32 v115, v157
	v_mov_b32_e32 v114, v157
	v_mov_b32_e32 v73, v157
	v_mov_b32_e32 v72, v157
	v_mov_b32_e32 v71, v157
	v_mov_b32_e32 v70, v157
	v_mov_b32_e32 v69, v157
	v_mov_b32_e32 v68, v157
	v_mov_b32_e32 v67, v157
	v_mov_b32_e32 v66, v157
	v_mov_b32_e32 v65, v157
	v_mov_b32_e32 v64, v157
	v_mov_b32_e32 v63, v157
	v_mov_b32_e32 v62, v157
	v_mov_b32_e32 v61, v157
	v_mov_b32_e32 v60, v157
	v_mov_b32_e32 v59, v157
	v_mov_b32_e32 v58, v157
	v_mov_b32_e32 v49, v157
	v_mov_b32_e32 v48, v157
	v_mov_b32_e32 v47, v157
	v_mov_b32_e32 v46, v157
	v_mov_b32_e32 v45, v157
	v_mov_b32_e32 v44, v157
	v_mov_b32_e32 v43, v157
	v_mov_b32_e32 v42, v157
	v_mov_b32_e32 v31, v157
	v_mov_b32_e32 v30, v157
	v_mov_b32_e32 v29, v157
	v_mov_b32_e32 v28, v157
	v_mov_b32_e32 v27, v157
	v_mov_b32_e32 v26, v157
	v_mov_b32_e32 v25, v157
	v_mov_b32_e32 v24, v157
	v_mov_b32_e32 v15, v157
	v_mov_b32_e32 v14, v157
	v_mov_b32_e32 v13, v157
	v_mov_b32_e32 v12, v157
	v_mov_b32_e32 v11, v157
	v_mov_b32_e32 v10, v157
	v_mov_b32_e32 v9, v157
	v_mov_b32_e32 v8, v157
	v_mov_b32_e32 v57, v157
	v_mov_b32_e32 v56, v157
	v_mov_b32_e32 v55, v157
	v_mov_b32_e32 v54, v157
	v_mov_b32_e32 v53, v157
	v_mov_b32_e32 v52, v157
	v_mov_b32_e32 v51, v157
	v_mov_b32_e32 v50, v157
	v_mov_b32_e32 v41, v157
	v_mov_b32_e32 v40, v157
	v_mov_b32_e32 v39, v157
	v_mov_b32_e32 v38, v157
	v_mov_b32_e32 v37, v157
	v_mov_b32_e32 v36, v157
	v_mov_b32_e32 v35, v157
	v_mov_b32_e32 v34, v157
	v_mov_b32_e32 v23, v157
	v_mov_b32_e32 v22, v157
	v_mov_b32_e32 v21, v157
	v_mov_b32_e32 v20, v157
	v_mov_b32_e32 v19, v157
	v_mov_b32_e32 v18, v157
	v_mov_b32_e32 v17, v157
	v_mov_b32_e32 v16, v157
	v_mov_b32_e32 v7, v157
	v_mov_b32_e32 v6, v157
	v_mov_b32_e32 v5, v157
	v_mov_b32_e32 v4, v157
	v_mov_b32_e32 v3, v157
	v_mov_b32_e32 v2, v157
	v_mov_b32_e32 v1, v157
	v_mov_b32_e32 v0, v157
	s_branch .LBB0_413

.Ljoin_B:
	s_add_i32 s10, 0, 0x18000
	v_add_u32_e32 v32, s10, v216
	s_add_i32 s52, 0, 0x1c000
	ds_read_b128 v[74:77], v32
	ds_read_b128 v[78:81], v32 offset:1024
	ds_read_b128 v[90:93], v32 offset:2048
	ds_read_b128 v[94:97], v32 offset:3072
	v_add_u32_e32 v32, s52, v216
	ds_read_b128 v[98:101], v32
	ds_read_b128 v[102:105], v32 offset:1024
	ds_read_b128 v[106:109], v32 offset:2048
	ds_read_b128 v[110:113], v32 offset:3072
	s_add_u32 s44, s44, s0
	s_addc_u32 s45, s45, s1
	s_mov_b32 m0, s9
	v_lshl_add_u64 v[248:249], s[44:45], 0, v[168:169]
	ds_read_b128 v[162:165], v218 offset:32768
	ds_read_b128 v[180:183], v218 offset:33792
	ds_read_b128 v[184:187], v218 offset:34816
	ds_read_b128 v[224:227], v218 offset:35840
	ds_read_b128 v[228:231], v218 offset:36864
	ds_read_b128 v[232:235], v218 offset:37888
	ds_read_b128 v[236:239], v218 offset:38912
	ds_read_b128 v[240:243], v218 offset:39936
	global_load_lds_dwordx4 v[248:249], off
	v_lshl_add_u64 v[248:249], s[44:45], 0, v[172:173]
	s_mov_b32 m0, s12
	s_nop 0
	global_load_lds_dwordx4 v[248:249], off
	s_waitcnt vmcnt(8)
	s_waitcnt lgkmcnt(0)
	s_barrier
	s_setprio 1
	s_waitcnt lgkmcnt(0)
	v_mfma_f32_16x16x32_bf16 v[154:157], v[74:77], v[162:165], v[154:157]
	v_mfma_f32_16x16x32_bf16 v[158:161], v[90:93], v[162:165], v[158:161]
	v_mfma_f32_16x16x32_bf16 v[142:145], v[74:77], v[184:187], v[142:145]
	v_mfma_f32_16x16x32_bf16 v[138:141], v[90:93], v[184:187], v[138:141]
	v_mfma_f32_16x16x32_bf16 v[126:129], v[74:77], v[228:231], v[126:129]
	v_mfma_f32_16x16x32_bf16 v[122:125], v[90:93], v[228:231], v[122:125]
	v_mfma_f32_16x16x32_bf16 v[86:89], v[74:77], v[236:239], v[86:89]
	v_mfma_f32_16x16x32_bf16 v[82:85], v[90:93], v[236:239], v[82:85]
	v_mfma_f32_16x16x32_bf16 v[154:157], v[78:81], v[180:183], v[154:157]
	v_mfma_f32_16x16x32_bf16 v[158:161], v[94:97], v[180:183], v[158:161]
	v_mfma_f32_16x16x32_bf16 v[142:145], v[78:81], v[224:227], v[142:145]
	v_mfma_f32_16x16x32_bf16 v[138:141], v[94:97], v[224:227], v[138:141]
	v_mfma_f32_16x16x32_bf16 v[126:129], v[78:81], v[232:235], v[126:129]
	v_mfma_f32_16x16x32_bf16 v[122:125], v[94:97], v[232:235], v[122:125]
	v_mfma_f32_16x16x32_bf16 v[86:89], v[78:81], v[240:243], v[86:89]
	v_mfma_f32_16x16x32_bf16 v[82:85], v[94:97], v[240:243], v[82:85]
	s_setprio 0
	s_setprio 1
	v_mfma_f32_16x16x32_bf16 v[150:153], v[98:101], v[162:165], v[150:153]
	v_mfma_f32_16x16x32_bf16 v[146:149], v[106:109], v[162:165], v[146:149]
	v_mfma_f32_16x16x32_bf16 v[134:137], v[98:101], v[184:187], v[134:137]
	v_mfma_f32_16x16x32_bf16 v[130:133], v[106:109], v[184:187], v[130:133]
	v_mfma_f32_16x16x32_bf16 v[118:121], v[98:101], v[228:231], v[118:121]
	v_mfma_f32_16x16x32_bf16 v[114:117], v[106:109], v[228:231], v[114:117]
	v_mfma_f32_16x16x32_bf16 v[70:73], v[98:101], v[236:239], v[70:73]
	v_mfma_f32_16x16x32_bf16 v[66:69], v[106:109], v[236:239], v[66:69]
	v_mfma_f32_16x16x32_bf16 v[150:153], v[102:105], v[180:183], v[150:153]
	v_mfma_f32_16x16x32_bf16 v[146:149], v[110:113], v[180:183], v[146:149]
	v_mfma_f32_16x16x32_bf16 v[134:137], v[102:105], v[224:227], v[134:137]
	v_mfma_f32_16x16x32_bf16 v[130:133], v[110:113], v[224:227], v[130:133]
	v_mfma_f32_16x16x32_bf16 v[118:121], v[102:105], v[232:235], v[118:121]
	v_mfma_f32_16x16x32_bf16 v[114:117], v[110:113], v[232:235], v[114:117]
	v_mfma_f32_16x16x32_bf16 v[70:73], v[102:105], v[240:243], v[70:73]
	v_mfma_f32_16x16x32_bf16 v[66:69], v[110:113], v[240:243], v[66:69]
	s_setprio 0
	s_barrier
	s_add_i32 s10, s10, s2
	v_lshl_add_u64 v[188:189], v[188:189], 0, s[56:57]
	s_mov_b32 m0, s10
	s_bitcmp1_b32 s99, 0
	s_cbranch_scc1 .Lh_r2
	ds_read_b128 v[162:165], v218 offset:49152
	ds_read_b128 v[180:183], v218 offset:50176
	ds_read_b128 v[184:187], v218 offset:51200
	ds_read_b128 v[224:227], v218 offset:52224
	ds_read_b128 v[228:231], v218 offset:53248
	ds_read_b128 v[232:235], v218 offset:54272
	ds_read_b128 v[236:239], v218 offset:55296
	ds_read_b128 v[240:243], v218 offset:56320

.LBB0_557:
	s_andn2_b64 vcc, exec, s[80:81]
	s_cbranch_vccnz .Lzs_A
	s_add_u32 s0, s0, 0x80
	s_addc_u32 s1, s1, 0
	s_add_u32 s44, s44, 0x100
	s_addc_u32 s45, s45, 0
	s_mov_b32 s42, 0
	s_add_i32 s49, s42, 2
	s_add_u32 vcc_lo, s0, 0x80
	s_addc_u32 s43, s1, 0
	s_add_i32 s10, 0, 0x10000
	s_cmp_eq_u32 s47, s42
	s_cselect_b32 s43, s35, s43
	s_cselect_b32 s42, s34, vcc_lo
	s_cselect_b32 vcc_hi, s29, s45
	s_cselect_b32 vcc_lo, s28, s44
	s_add_i32 s52, 0, 0x14000
	v_add_u32_e32 v86, s10, v172
	v_add_u32_e32 v175, s52, v172
	ds_read_b128 v[66:69], v86
	ds_read_b128 v[70:73], v86 offset:1024
	ds_read_b128 v[82:85], v86 offset:2048
	ds_read_b128 v[86:89], v86 offset:3072
	ds_read_b128 v[146:149], v175
	ds_read_b128 v[162:165], v175 offset:1024
	ds_read_b128 v[168:171], v175 offset:2048
	ds_read_b128 v[176:179], v175 offset:3072
	v_lshl_add_u64 v[188:189], s[0:1], 0, v[158:159]
	s_add_i32 m0, s7, 0xc000
	ds_read_b128 v[180:183], v174
	ds_read_b128 v[184:187], v174 offset:1024
	ds_read_b128 v[216:219], v174 offset:2048
	ds_read_b128 v[224:227], v174 offset:3072
	ds_read_b128 v[228:231], v174 offset:4096
	ds_read_b128 v[232:235], v174 offset:5120
	ds_read_b128 v[236:239], v174 offset:6144
	ds_read_b128 v[240:243], v174 offset:7168
	global_load_lds_dwordx4 v[188:189], off
	v_lshl_add_u64 v[188:189], s[0:1], 0, v[160:161]
	s_add_i32 m0, s7, 0xe000
	s_nop 0
	global_load_lds_dwordx4 v[188:189], off
	s_waitcnt vmcnt(8)
	s_waitcnt lgkmcnt(0)
	s_barrier
	s_setprio 1
	s_waitcnt lgkmcnt(0)
	v_mfma_f32_16x16x32_bf16 v[138:141], v[66:69], v[180:183], 0
	v_mfma_f32_16x16x32_bf16 v[142:145], v[82:85], v[180:183], 0
	v_mfma_f32_16x16x32_bf16 v[126:129], v[66:69], v[216:219], 0
	v_mfma_f32_16x16x32_bf16 v[122:125], v[82:85], v[216:219], 0
	v_mfma_f32_16x16x32_bf16 v[110:113], v[66:69], v[228:231], 0
	v_mfma_f32_16x16x32_bf16 v[106:109], v[82:85], v[228:231], 0
	v_mfma_f32_16x16x32_bf16 v[94:97], v[66:69], v[236:239], 0
	v_mfma_f32_16x16x32_bf16 v[90:93], v[82:85], v[236:239], 0
	v_mfma_f32_16x16x32_bf16 v[138:141], v[70:73], v[184:187], v[138:141]
	v_mfma_f32_16x16x32_bf16 v[142:145], v[86:89], v[184:187], v[142:145]
	v_mfma_f32_16x16x32_bf16 v[126:129], v[70:73], v[224:227], v[126:129]
	v_mfma_f32_16x16x32_bf16 v[122:125], v[86:89], v[224:227], v[122:125]
	v_mfma_f32_16x16x32_bf16 v[110:113], v[70:73], v[232:235], v[110:113]
	v_mfma_f32_16x16x32_bf16 v[106:109], v[86:89], v[232:235], v[106:109]
	v_mfma_f32_16x16x32_bf16 v[94:97], v[70:73], v[240:243], v[94:97]
	v_mfma_f32_16x16x32_bf16 v[90:93], v[86:89], v[240:243], v[90:93]
	s_setprio 0
	s_setprio 1
	v_mfma_f32_16x16x32_bf16 v[134:137], v[146:149], v[180:183], 0
	v_mfma_f32_16x16x32_bf16 v[130:133], v[168:171], v[180:183], 0
	v_mfma_f32_16x16x32_bf16 v[118:121], v[146:149], v[216:219], 0
	v_mfma_f32_16x16x32_bf16 v[114:117], v[168:171], v[216:219], 0
	v_mfma_f32_16x16x32_bf16 v[102:105], v[146:149], v[228:231], 0
	v_mfma_f32_16x16x32_bf16 v[98:101], v[168:171], v[228:231], 0
	v_mfma_f32_16x16x32_bf16 v[78:81], v[146:149], v[236:239], 0
	v_mfma_f32_16x16x32_bf16 v[74:77], v[168:171], v[236:239], 0
	v_mfma_f32_16x16x32_bf16 v[134:137], v[162:165], v[184:187], v[134:137]
	v_mfma_f32_16x16x32_bf16 v[130:133], v[176:179], v[184:187], v[130:133]
	v_mfma_f32_16x16x32_bf16 v[118:121], v[162:165], v[224:227], v[118:121]
	v_mfma_f32_16x16x32_bf16 v[114:117], v[176:179], v[224:227], v[114:117]
	v_mfma_f32_16x16x32_bf16 v[102:105], v[162:165], v[232:235], v[102:105]
	v_mfma_f32_16x16x32_bf16 v[98:101], v[176:179], v[232:235], v[98:101]
	v_mfma_f32_16x16x32_bf16 v[78:81], v[162:165], v[240:243], v[78:81]
	v_mfma_f32_16x16x32_bf16 v[74:77], v[176:179], v[240:243], v[74:77]
	s_setprio 0
	s_barrier
	s_add_i32 s10, s10, s94
	v_lshl_add_u64 v[188:189], vcc, 0, v[32:33]
	s_mov_b32 m0, s10
	ds_read_b128 v[180:183], v174 offset:16384
	ds_read_b128 v[184:187], v174 offset:17408
	ds_read_b128 v[216:219], v174 offset:18432
	ds_read_b128 v[224:227], v174 offset:19456
	ds_read_b128 v[228:231], v174 offset:20480
	ds_read_b128 v[232:235], v174 offset:21504
	ds_read_b128 v[236:239], v174 offset:22528
	ds_read_b128 v[240:243], v174 offset:23552
	global_load_lds_dwordx4 v[188:189], off
	s_add_i32 m0, s10, 0x2000
	v_lshl_add_u64 v[244:245], vcc, 0, v[154:155]
	s_add_u32 vcc_lo, vcc_lo, s96
	s_addc_u32 vcc_hi, vcc_hi, s97
	s_add_i32 s10, s52, s94
	global_load_lds_dwordx4 v[244:245], off
	v_lshl_add_u64 v[246:247], vcc, 0, v[32:33]
	s_mov_b32 m0, s10
	v_lshl_add_u64 v[248:249], vcc, 0, v[154:155]
	global_load_lds_dwordx4 v[246:247], off
	s_add_i32 m0, s10, 0x2000
	v_lshl_add_u64 v[202:203], s[42:43], 0, v[150:151]
	global_load_lds_dwordx4 v[248:249], off
	s_mov_b32 m0, s7
	v_lshl_add_u64 v[212:213], s[42:43], 0, v[152:153]
	global_load_lds_dwordx4 v[202:203], off
	s_mov_b32 m0, s2
	s_nop 0
	global_load_lds_dwordx4 v[212:213], off
	s_waitcnt vmcnt(8)
	s_waitcnt lgkmcnt(0)
	s_barrier
	s_setprio 1
	s_waitcnt lgkmcnt(0)
	v_mfma_f32_16x16x32_bf16 v[62:65], v[66:69], v[180:183], 0
	v_mfma_f32_16x16x32_bf16 v[58:61], v[82:85], v[180:183], 0
	v_mfma_f32_16x16x32_bf16 v[46:49], v[66:69], v[216:219], 0
	v_mfma_f32_16x16x32_bf16 v[42:45], v[82:85], v[216:219], 0
	v_mfma_f32_16x16x32_bf16 v[28:31], v[66:69], v[228:231], 0
	v_mfma_f32_16x16x32_bf16 v[24:27], v[82:85], v[228:231], 0
	v_mfma_f32_16x16x32_bf16 v[12:15], v[66:69], v[236:239], 0
	v_mfma_f32_16x16x32_bf16 v[8:11], v[82:85], v[236:239], 0
	v_mfma_f32_16x16x32_bf16 v[62:65], v[70:73], v[184:187], v[62:65]
	v_mfma_f32_16x16x32_bf16 v[58:61], v[86:89], v[184:187], v[58:61]
	v_mfma_f32_16x16x32_bf16 v[46:49], v[70:73], v[224:227], v[46:49]
	v_mfma_f32_16x16x32_bf16 v[42:45], v[86:89], v[224:227], v[42:45]
	v_mfma_f32_16x16x32_bf16 v[28:31], v[70:73], v[232:235], v[28:31]
	v_mfma_f32_16x16x32_bf16 v[24:27], v[86:89], v[232:235], v[24:27]
	v_mfma_f32_16x16x32_bf16 v[12:15], v[70:73], v[240:243], v[12:15]
	v_mfma_f32_16x16x32_bf16 v[8:11], v[86:89], v[240:243], v[8:11]
	s_setprio 0
	s_setprio 1
	v_mfma_f32_16x16x32_bf16 v[54:57], v[146:149], v[180:183], 0
	v_mfma_f32_16x16x32_bf16 v[50:53], v[168:171], v[180:183], 0
	v_mfma_f32_16x16x32_bf16 v[38:41], v[146:149], v[216:219], 0
	v_mfma_f32_16x16x32_bf16 v[34:37], v[168:171], v[216:219], 0
	v_mfma_f32_16x16x32_bf16 v[20:23], v[146:149], v[228:231], 0
	v_mfma_f32_16x16x32_bf16 v[16:19], v[168:171], v[228:231], 0
	v_mfma_f32_16x16x32_bf16 v[4:7], v[146:149], v[236:239], 0
	v_mfma_f32_16x16x32_bf16 v[0:3], v[168:171], v[236:239], 0
	v_mfma_f32_16x16x32_bf16 v[54:57], v[162:165], v[184:187], v[54:57]
	v_mfma_f32_16x16x32_bf16 v[50:53], v[176:179], v[184:187], v[50:53]
	v_mfma_f32_16x16x32_bf16 v[38:41], v[162:165], v[224:227], v[38:41]
	v_mfma_f32_16x16x32_bf16 v[34:37], v[176:179], v[224:227], v[34:37]
	v_mfma_f32_16x16x32_bf16 v[20:23], v[162:165], v[232:235], v[20:23]
	v_mfma_f32_16x16x32_bf16 v[16:19], v[176:179], v[232:235], v[16:19]
	v_mfma_f32_16x16x32_bf16 v[4:7], v[162:165], v[240:243], v[4:7]
	v_mfma_f32_16x16x32_bf16 v[0:3], v[176:179], v[240:243], v[0:3]
	s_setprio 0
	s_barrier
	s_branch .Ljoin_A
.Lzs_A:
	v_mov_b32_e32 v141, 0
	v_mov_b32_e32 v140, v141
	v_mov_b32_e32 v139, v141
	v_mov_b32_e32 v138, v141
	v_mov_b32_e32 v145, v141
	v_mov_b32_e32 v144, v141
	v_mov_b32_e32 v143, v141
	v_mov_b32_e32 v142, v141
	v_mov_b32_e32 v129, v141
	v_mov_b32_e32 v128, v141
	v_mov_b32_e32 v127, v141
	v_mov_b32_e32 v126, v141
	v_mov_b32_e32 v125, v141
	v_mov_b32_e32 v124, v141
	v_mov_b32_e32 v123, v141
	v_mov_b32_e32 v122, v141
	v_mov_b32_e32 v113, v141
	v_mov_b32_e32 v112, v141
	v_mov_b32_e32 v111, v141
	v_mov_b32_e32 v110, v141
	v_mov_b32_e32 v109, v141
	v_mov_b32_e32 v108, v141
	v_mov_b32_e32 v107, v141
	v_mov_b32_e32 v106, v141
	v_mov_b32_e32 v97, v141
	v_mov_b32_e32 v96, v141
	v_mov_b32_e32 v95, v141
	v_mov_b32_e32 v94, v141
	v_mov_b32_e32 v93, v141
	v_mov_b32_e32 v92, v141
	v_mov_b32_e32 v91, v141
	v_mov_b32_e32 v90, v141
	v_mov_b32_e32 v137, v141
	v_mov_b32_e32 v136, v141
	v_mov_b32_e32 v135, v141
	v_mov_b32_e32 v134, v141
	v_mov_b32_e32 v133, v141
	v_mov_b32_e32 v132, v141
	v_mov_b32_e32 v131, v141
	v_mov_b32_e32 v130, v141
	v_mov_b32_e32 v121, v141
	v_mov_b32_e32 v120, v141
	v_mov_b32_e32 v119, v141
	v_mov_b32_e32 v118, v141
	v_mov_b32_e32 v117, v141
	v_mov_b32_e32 v116, v141
	v_mov_b32_e32 v115, v141
	v_mov_b32_e32 v114, v141
	v_mov_b32_e32 v105, v141
	v_mov_b32_e32 v104, v141
	v_mov_b32_e32 v103, v141
	v_mov_b32_e32 v102, v141
	v_mov_b32_e32 v101, v141
	v_mov_b32_e32 v100, v141
	v_mov_b32_e32 v99, v141
	v_mov_b32_e32 v98, v141
	v_mov_b32_e32 v81, v141
	v_mov_b32_e32 v80, v141
	v_mov_b32_e32 v79, v141
	v_mov_b32_e32 v78, v141
	v_mov_b32_e32 v77, v141
	v_mov_b32_e32 v76, v141
	v_mov_b32_e32 v75, v141
	v_mov_b32_e32 v74, v141
	v_mov_b32_e32 v65, v141
	v_mov_b32_e32 v64, v141
	v_mov_b32_e32 v63, v141
	v_mov_b32_e32 v62, v141
	v_mov_b32_e32 v61, v141
	v_mov_b32_e32 v60, v141
	v_mov_b32_e32 v59, v141
	v_mov_b32_e32 v58, v141
	v_mov_b32_e32 v49, v141
	v_mov_b32_e32 v48, v141
	v_mov_b32_e32 v47, v141
	v_mov_b32_e32 v46, v141
	v_mov_b32_e32 v45, v141
	v_mov_b32_e32 v44, v141
	v_mov_b32_e32 v43, v141
	v_mov_b32_e32 v42, v141
	v_mov_b32_e32 v31, v141
	v_mov_b32_e32 v30, v141
	v_mov_b32_e32 v29, v141
	v_mov_b32_e32 v28, v141
	v_mov_b32_e32 v27, v141
	v_mov_b32_e32 v26, v141
	v_mov_b32_e32 v25, v141
	v_mov_b32_e32 v24, v141
	v_mov_b32_e32 v15, v141
	v_mov_b32_e32 v14, v141
	v_mov_b32_e32 v13, v141
	v_mov_b32_e32 v12, v141
	v_mov_b32_e32 v11, v141
	v_mov_b32_e32 v10, v141
	v_mov_b32_e32 v9, v141
	v_mov_b32_e32 v8, v141
	v_mov_b32_e32 v57, v141
	v_mov_b32_e32 v56, v141
	v_mov_b32_e32 v55, v141
	v_mov_b32_e32 v54, v141
	v_mov_b32_e32 v53, v141
	v_mov_b32_e32 v52, v141
	v_mov_b32_e32 v51, v141
	v_mov_b32_e32 v50, v141
	v_mov_b32_e32 v41, v141
	v_mov_b32_e32 v40, v141
	v_mov_b32_e32 v39, v141
	v_mov_b32_e32 v38, v141
	v_mov_b32_e32 v37, v141
	v_mov_b32_e32 v36, v141
	v_mov_b32_e32 v35, v141
	v_mov_b32_e32 v34, v141
	v_mov_b32_e32 v23, v141
	v_mov_b32_e32 v22, v141
	v_mov_b32_e32 v21, v141
	v_mov_b32_e32 v20, v141
	v_mov_b32_e32 v19, v141
	v_mov_b32_e32 v18, v141
	v_mov_b32_e32 v17, v141
	v_mov_b32_e32 v16, v141
	v_mov_b32_e32 v7, v141
	v_mov_b32_e32 v6, v141
	v_mov_b32_e32 v5, v141
	v_mov_b32_e32 v4, v141
	v_mov_b32_e32 v3, v141
	v_mov_b32_e32 v2, v141
	v_mov_b32_e32 v1, v141
	v_mov_b32_e32 v0, v141
	s_branch .LBB0_561
.LBB0_559:
	s_add_i32 s49, s42, 2
	s_add_u32 vcc_lo, s0, 0x80
	s_addc_u32 s43, s1, 0
	s_add_i32 s10, 0, 0x10000
	s_cmp_eq_u32 s47, s42
	s_cselect_b32 s43, s35, s43
	s_cselect_b32 s42, s34, vcc_lo
	s_cselect_b32 vcc_hi, s29, s45
	s_cselect_b32 vcc_lo, s28, s44
	s_add_i32 s52, 0, 0x14000
	v_add_u32_e32 v86, s10, v172
	v_add_u32_e32 v175, s52, v172
	ds_read_b128 v[66:69], v86
	ds_read_b128 v[70:73], v86 offset:1024
	ds_read_b128 v[82:85], v86 offset:2048
	ds_read_b128 v[86:89], v86 offset:3072
	ds_read_b128 v[146:149], v175
	ds_read_b128 v[162:165], v175 offset:1024
	ds_read_b128 v[168:171], v175 offset:2048
	ds_read_b128 v[176:179], v175 offset:3072
	v_lshl_add_u64 v[188:189], s[0:1], 0, v[158:159]
	s_add_i32 m0, s7, 0xc000
	ds_read_b128 v[180:183], v174
	ds_read_b128 v[184:187], v174 offset:1024
	ds_read_b128 v[216:219], v174 offset:2048
	ds_read_b128 v[224:227], v174 offset:3072
	ds_read_b128 v[228:231], v174 offset:4096
	ds_read_b128 v[232:235], v174 offset:5120
	ds_read_b128 v[236:239], v174 offset:6144
	ds_read_b128 v[240:243], v174 offset:7168
	global_load_lds_dwordx4 v[188:189], off
	v_lshl_add_u64 v[188:189], s[0:1], 0, v[160:161]
	s_add_i32 m0, s7, 0xe000
	s_nop 0
	global_load_lds_dwordx4 v[188:189], off
	s_waitcnt vmcnt(8)
	s_waitcnt lgkmcnt(0)
	s_barrier
	s_setprio 1
	s_waitcnt lgkmcnt(0)
	s_nop 0
	v_mfma_f32_16x16x32_bf16 v[138:141], v[66:69], v[180:183], v[138:141]
	v_mfma_f32_16x16x32_bf16 v[142:145], v[82:85], v[180:183], v[142:145]
	v_mfma_f32_16x16x32_bf16 v[126:129], v[66:69], v[216:219], v[126:129]
	v_mfma_f32_16x16x32_bf16 v[122:125], v[82:85], v[216:219], v[122:125]
	v_mfma_f32_16x16x32_bf16 v[110:113], v[66:69], v[228:231], v[110:113]
	v_mfma_f32_16x16x32_bf16 v[106:109], v[82:85], v[228:231], v[106:109]
	v_mfma_f32_16x16x32_bf16 v[94:97], v[66:69], v[236:239], v[94:97]
	v_mfma_f32_16x16x32_bf16 v[90:93], v[82:85], v[236:239], v[90:93]
	v_mfma_f32_16x16x32_bf16 v[138:141], v[70:73], v[184:187], v[138:141]
	v_mfma_f32_16x16x32_bf16 v[142:145], v[86:89], v[184:187], v[142:145]
	v_mfma_f32_16x16x32_bf16 v[126:129], v[70:73], v[224:227], v[126:129]
	v_mfma_f32_16x16x32_bf16 v[122:125], v[86:89], v[224:227], v[122:125]
	v_mfma_f32_16x16x32_bf16 v[110:113], v[70:73], v[232:235], v[110:113]
	v_mfma_f32_16x16x32_bf16 v[106:109], v[86:89], v[232:235], v[106:109]
	v_mfma_f32_16x16x32_bf16 v[94:97], v[70:73], v[240:243], v[94:97]
	v_mfma_f32_16x16x32_bf16 v[90:93], v[86:89], v[240:243], v[90:93]
	s_setprio 0
	s_setprio 1
	v_mfma_f32_16x16x32_bf16 v[134:137], v[146:149], v[180:183], v[134:137]
	v_mfma_f32_16x16x32_bf16 v[130:133], v[168:171], v[180:183], v[130:133]
	v_mfma_f32_16x16x32_bf16 v[118:121], v[146:149], v[216:219], v[118:121]
	v_mfma_f32_16x16x32_bf16 v[114:117], v[168:171], v[216:219], v[114:117]
	v_mfma_f32_16x16x32_bf16 v[102:105], v[146:149], v[228:231], v[102:105]
	v_mfma_f32_16x16x32_bf16 v[98:101], v[168:171], v[228:231], v[98:101]
	v_mfma_f32_16x16x32_bf16 v[78:81], v[146:149], v[236:239], v[78:81]
	v_mfma_f32_16x16x32_bf16 v[74:77], v[168:171], v[236:239], v[74:77]
	v_mfma_f32_16x16x32_bf16 v[134:137], v[162:165], v[184:187], v[134:137]
	v_mfma_f32_16x16x32_bf16 v[130:133], v[176:179], v[184:187], v[130:133]
	v_mfma_f32_16x16x32_bf16 v[118:121], v[162:165], v[224:227], v[118:121]
	v_mfma_f32_16x16x32_bf16 v[114:117], v[176:179], v[224:227], v[114:117]
	v_mfma_f32_16x16x32_bf16 v[102:105], v[162:165], v[232:235], v[102:105]
	v_mfma_f32_16x16x32_bf16 v[98:101], v[176:179], v[232:235], v[98:101]
	v_mfma_f32_16x16x32_bf16 v[78:81], v[162:165], v[240:243], v[78:81]
	v_mfma_f32_16x16x32_bf16 v[74:77], v[176:179], v[240:243], v[74:77]
	s_setprio 0
	s_barrier
	s_add_i32 s10, s10, s94
	v_lshl_add_u64 v[188:189], vcc, 0, v[32:33]
	s_mov_b32 m0, s10
	ds_read_b128 v[180:183], v174 offset:16384
	ds_read_b128 v[184:187], v174 offset:17408
	ds_read_b128 v[216:219], v174 offset:18432
	ds_read_b128 v[224:227], v174 offset:19456
	ds_read_b128 v[228:231], v174 offset:20480
	ds_read_b128 v[232:235], v174 offset:21504
	ds_read_b128 v[236:239], v174 offset:22528
	ds_read_b128 v[240:243], v174 offset:23552
	global_load_lds_dwordx4 v[188:189], off
	s_add_i32 m0, s10, 0x2000
	v_lshl_add_u64 v[244:245], vcc, 0, v[154:155]
	s_add_u32 vcc_lo, vcc_lo, s96
	s_addc_u32 vcc_hi, vcc_hi, s97
	s_add_i32 s10, s52, s94
	global_load_lds_dwordx4 v[244:245], off
	v_lshl_add_u64 v[246:247], vcc, 0, v[32:33]
	s_mov_b32 m0, s10
	v_lshl_add_u64 v[248:249], vcc, 0, v[154:155]
	global_load_lds_dwordx4 v[246:247], off
	s_add_i32 m0, s10, 0x2000
	v_lshl_add_u64 v[202:203], s[42:43], 0, v[150:151]
	global_load_lds_dwordx4 v[248:249], off
	s_mov_b32 m0, s7
	v_lshl_add_u64 v[212:213], s[42:43], 0, v[152:153]
	global_load_lds_dwordx4 v[202:203], off
	s_mov_b32 m0, s2
	s_nop 0
	global_load_lds_dwordx4 v[212:213], off
	s_waitcnt vmcnt(8)
	s_waitcnt lgkmcnt(0)
	s_barrier
	s_setprio 1
	s_waitcnt lgkmcnt(0)
	v_mfma_f32_16x16x32_bf16 v[62:65], v[66:69], v[180:183], v[62:65]
	v_mfma_f32_16x16x32_bf16 v[58:61], v[82:85], v[180:183], v[58:61]
	v_mfma_f32_16x16x32_bf16 v[46:49], v[66:69], v[216:219], v[46:49]
	v_mfma_f32_16x16x32_bf16 v[42:45], v[82:85], v[216:219], v[42:45]
	v_mfma_f32_16x16x32_bf16 v[28:31], v[66:69], v[228:231], v[28:31]
	v_mfma_f32_16x16x32_bf16 v[24:27], v[82:85], v[228:231], v[24:27]
	v_mfma_f32_16x16x32_bf16 v[12:15], v[66:69], v[236:239], v[12:15]
	v_mfma_f32_16x16x32_bf16 v[8:11], v[82:85], v[236:239], v[8:11]
	v_mfma_f32_16x16x32_bf16 v[62:65], v[70:73], v[184:187], v[62:65]
	v_mfma_f32_16x16x32_bf16 v[58:61], v[86:89], v[184:187], v[58:61]
	v_mfma_f32_16x16x32_bf16 v[46:49], v[70:73], v[224:227], v[46:49]
	v_mfma_f32_16x16x32_bf16 v[42:45], v[86:89], v[224:227], v[42:45]
	v_mfma_f32_16x16x32_bf16 v[28:31], v[70:73], v[232:235], v[28:31]
	v_mfma_f32_16x16x32_bf16 v[24:27], v[86:89], v[232:235], v[24:27]
	v_mfma_f32_16x16x32_bf16 v[12:15], v[70:73], v[240:243], v[12:15]
	v_mfma_f32_16x16x32_bf16 v[8:11], v[86:89], v[240:243], v[8:11]
	s_setprio 0
	s_setprio 1
	v_mfma_f32_16x16x32_bf16 v[54:57], v[146:149], v[180:183], v[54:57]
	v_mfma_f32_16x16x32_bf16 v[50:53], v[168:171], v[180:183], v[50:53]
	v_mfma_f32_16x16x32_bf16 v[38:41], v[146:149], v[216:219], v[38:41]
	v_mfma_f32_16x16x32_bf16 v[34:37], v[168:171], v[216:219], v[34:37]
	v_mfma_f32_16x16x32_bf16 v[20:23], v[146:149], v[228:231], v[20:23]
	v_mfma_f32_16x16x32_bf16 v[16:19], v[168:171], v[228:231], v[16:19]
	v_mfma_f32_16x16x32_bf16 v[4:7], v[146:149], v[236:239], v[4:7]
	v_mfma_f32_16x16x32_bf16 v[0:3], v[168:171], v[236:239], v[0:3]
	v_mfma_f32_16x16x32_bf16 v[54:57], v[162:165], v[184:187], v[54:57]
	v_mfma_f32_16x16x32_bf16 v[50:53], v[176:179], v[184:187], v[50:53]
	v_mfma_f32_16x16x32_bf16 v[38:41], v[162:165], v[224:227], v[38:41]
	v_mfma_f32_16x16x32_bf16 v[34:37], v[176:179], v[224:227], v[34:37]
	v_mfma_f32_16x16x32_bf16 v[20:23], v[162:165], v[232:235], v[20:23]
	v_mfma_f32_16x16x32_bf16 v[16:19], v[176:179], v[232:235], v[16:19]
	v_mfma_f32_16x16x32_bf16 v[4:7], v[162:165], v[240:243], v[4:7]
	v_mfma_f32_16x16x32_bf16 v[0:3], v[176:179], v[240:243], v[0:3]
	s_setprio 0
	s_barrier
.Ljoin_A:
	s_add_i32 s10, 0, 0x18000
	s_add_i32 s52, 0, 0x1c000
	v_add_u32_e32 v86, s10, v172
	v_add_u32_e32 v175, s52, v172
	ds_read_b128 v[66:69], v86
	ds_read_b128 v[70:73], v86 offset:1024
	ds_read_b128 v[82:85], v86 offset:2048
	ds_read_b128 v[86:89], v86 offset:3072
	ds_read_b128 v[146:149], v175
	ds_read_b128 v[162:165], v175 offset:1024
	ds_read_b128 v[168:171], v175 offset:2048
	ds_read_b128 v[176:179], v175 offset:3072
	s_add_u32 s42, s42, s96
	s_addc_u32 s43, s43, s97
	s_mov_b32 m0, s3
	v_lshl_add_u64 v[204:205], s[42:43], 0, v[150:151]
	ds_read_b128 v[180:183], v174 offset:32768
	ds_read_b128 v[184:187], v174 offset:33792
	ds_read_b128 v[216:219], v174 offset:34816
	ds_read_b128 v[224:227], v174 offset:35840
	ds_read_b128 v[228:231], v174 offset:36864
	ds_read_b128 v[232:235], v174 offset:37888
	ds_read_b128 v[236:239], v174 offset:38912
	ds_read_b128 v[240:243], v174 offset:39936
	global_load_lds_dwordx4 v[204:205], off
	v_lshl_add_u64 v[204:205], s[42:43], 0, v[152:153]
	s_mov_b32 m0, s17
	s_nop 0
	global_load_lds_dwordx4 v[204:205], off
	s_waitcnt vmcnt(8)
	s_waitcnt lgkmcnt(0)
	s_barrier
	s_setprio 1
	s_waitcnt lgkmcnt(0)
	v_mfma_f32_16x16x32_bf16 v[138:141], v[66:69], v[180:183], v[138:141]
	v_mfma_f32_16x16x32_bf16 v[142:145], v[82:85], v[180:183], v[142:145]
	v_mfma_f32_16x16x32_bf16 v[126:129], v[66:69], v[216:219], v[126:129]
	v_mfma_f32_16x16x32_bf16 v[122:125], v[82:85], v[216:219], v[122:125]
	v_mfma_f32_16x16x32_bf16 v[110:113], v[66:69], v[228:231], v[110:113]
	v_mfma_f32_16x16x32_bf16 v[106:109], v[82:85], v[228:231], v[106:109]
	v_mfma_f32_16x16x32_bf16 v[94:97], v[66:69], v[236:239], v[94:97]
	v_mfma_f32_16x16x32_bf16 v[90:93], v[82:85], v[236:239], v[90:93]
	v_mfma_f32_16x16x32_bf16 v[138:141], v[70:73], v[184:187], v[138:141]
	v_mfma_f32_16x16x32_bf16 v[142:145], v[86:89], v[184:187], v[142:145]
	v_mfma_f32_16x16x32_bf16 v[126:129], v[70:73], v[224:227], v[126:129]
	v_mfma_f32_16x16x32_bf16 v[122:125], v[86:89], v[224:227], v[122:125]
	v_mfma_f32_16x16x32_bf16 v[110:113], v[70:73], v[232:235], v[110:113]
	v_mfma_f32_16x16x32_bf16 v[106:109], v[86:89], v[232:235], v[106:109]
	v_mfma_f32_16x16x32_bf16 v[94:97], v[70:73], v[240:243], v[94:97]
	v_mfma_f32_16x16x32_bf16 v[90:93], v[86:89], v[240:243], v[90:93]
	s_setprio 0
	s_setprio 1
	v_mfma_f32_16x16x32_bf16 v[134:137], v[146:149], v[180:183], v[134:137]
	v_mfma_f32_16x16x32_bf16 v[130:133], v[168:171], v[180:183], v[130:133]
	v_mfma_f32_16x16x32_bf16 v[118:121], v[146:149], v[216:219], v[118:121]
	v_mfma_f32_16x16x32_bf16 v[114:117], v[168:171], v[216:219], v[114:117]
	v_mfma_f32_16x16x32_bf16 v[102:105], v[146:149], v[228:231], v[102:105]
	v_mfma_f32_16x16x32_bf16 v[98:101], v[168:171], v[228:231], v[98:101]
	v_mfma_f32_16x16x32_bf16 v[78:81], v[146:149], v[236:239], v[78:81]
	v_mfma_f32_16x16x32_bf16 v[74:77], v[168:171], v[236:239], v[74:77]
	v_mfma_f32_16x16x32_bf16 v[134:137], v[162:165], v[184:187], v[134:137]
	v_mfma_f32_16x16x32_bf16 v[130:133], v[176:179], v[184:187], v[130:133]
	v_mfma_f32_16x16x32_bf16 v[118:121], v[162:165], v[224:227], v[118:121]
	v_mfma_f32_16x16x32_bf16 v[114:117], v[176:179], v[224:227], v[114:117]
	v_mfma_f32_16x16x32_bf16 v[102:105], v[162:165], v[232:235], v[102:105]
	v_mfma_f32_16x16x32_bf16 v[98:101], v[176:179], v[232:235], v[98:101]
	v_mfma_f32_16x16x32_bf16 v[78:81], v[162:165], v[240:243], v[78:81]
	v_mfma_f32_16x16x32_bf16 v[74:77], v[176:179], v[240:243], v[74:77]
	s_setprio 0
	s_barrier
	s_add_i32 s10, s10, s94
	v_lshl_add_u64 v[188:189], v[188:189], 0, s[56:57]
	s_mov_b32 m0, s10
	ds_read_b128 v[180:183], v174 offset:49152
	ds_read_b128 v[184:187], v174 offset:50176
	ds_read_b128 v[216:219], v174 offset:51200
	ds_read_b128 v[224:227], v174 offset:52224
	ds_read_b128 v[228:231], v174 offset:53248
	ds_read_b128 v[232:235], v174 offset:54272
	ds_read_b128 v[236:239], v174 offset:55296
	ds_read_b128 v[240:243], v174 offset:56320
	global_load_lds_dwordx4 v[188:189], off
	v_lshl_add_u64 v[188:189], v[244:245], 0, s[56:57]
	s_add_i32 m0, s10, 0x2000
	s_add_i32 s10, s52, s94
	global_load_lds_dwordx4 v[188:189], off
	v_lshl_add_u64 v[188:189], v[246:247], 0, s[56:57]
	s_mov_b32 m0, s10
	s_nop 0
	global_load_lds_dwordx4 v[188:189], off
	v_lshl_add_u64 v[188:189], v[248:249], 0, s[56:57]
	s_add_i32 m0, s10, 0x2000
	s_nop 0
	global_load_lds_dwordx4 v[188:189], off
	v_lshl_add_u64 v[188:189], v[202:203], 0, s[56:57]
	s_mov_b32 m0, s13
	s_nop 0
	global_load_lds_dwordx4 v[188:189], off
	v_lshl_add_u64 v[188:189], v[212:213], 0, s[56:57]
	s_mov_b32 m0, s46
	s_nop 0
	global_load_lds_dwordx4 v[188:189], off
	s_waitcnt vmcnt(8)
	s_waitcnt lgkmcnt(0)
	s_barrier
	s_setprio 1
	s_waitcnt lgkmcnt(0)
	s_nop 0
	v_mfma_f32_16x16x32_bf16 v[62:65], v[66:69], v[180:183], v[62:65]
	v_mfma_f32_16x16x32_bf16 v[58:61], v[82:85], v[180:183], v[58:61]
	v_mfma_f32_16x16x32_bf16 v[46:49], v[66:69], v[216:219], v[46:49]
	v_mfma_f32_16x16x32_bf16 v[42:45], v[82:85], v[216:219], v[42:45]
	v_mfma_f32_16x16x32_bf16 v[28:31], v[66:69], v[228:231], v[28:31]
	v_mfma_f32_16x16x32_bf16 v[24:27], v[82:85], v[228:231], v[24:27]
	v_mfma_f32_16x16x32_bf16 v[12:15], v[66:69], v[236:239], v[12:15]
	v_mfma_f32_16x16x32_bf16 v[8:11], v[82:85], v[236:239], v[8:11]
	v_mfma_f32_16x16x32_bf16 v[62:65], v[70:73], v[184:187], v[62:65]
	v_mfma_f32_16x16x32_bf16 v[58:61], v[86:89], v[184:187], v[58:61]
	v_mfma_f32_16x16x32_bf16 v[46:49], v[70:73], v[224:227], v[46:49]
	v_mfma_f32_16x16x32_bf16 v[42:45], v[86:89], v[224:227], v[42:45]
	v_mfma_f32_16x16x32_bf16 v[28:31], v[70:73], v[232:235], v[28:31]
	v_mfma_f32_16x16x32_bf16 v[24:27], v[86:89], v[232:235], v[24:27]
	v_mfma_f32_16x16x32_bf16 v[12:15], v[70:73], v[240:243], v[12:15]
	v_mfma_f32_16x16x32_bf16 v[8:11], v[86:89], v[240:243], v[8:11]
	s_setprio 0
	s_setprio 1
	v_mfma_f32_16x16x32_bf16 v[54:57], v[146:149], v[180:183], v[54:57]
	v_mfma_f32_16x16x32_bf16 v[50:53], v[168:171], v[180:183], v[50:53]
	v_mfma_f32_16x16x32_bf16 v[38:41], v[146:149], v[216:219], v[38:41]
	v_mfma_f32_16x16x32_bf16 v[34:37], v[168:171], v[216:219], v[34:37]
	v_mfma_f32_16x16x32_bf16 v[20:23], v[146:149], v[228:231], v[20:23]
	v_mfma_f32_16x16x32_bf16 v[16:19], v[168:171], v[228:231], v[16:19]
	v_mfma_f32_16x16x32_bf16 v[4:7], v[146:149], v[236:239], v[4:7]
	v_mfma_f32_16x16x32_bf16 v[0:3], v[168:171], v[236:239], v[0:3]
	v_mfma_f32_16x16x32_bf16 v[54:57], v[162:165], v[184:187], v[54:57]
	v_mfma_f32_16x16x32_bf16 v[50:53], v[176:179], v[184:187], v[50:53]
	v_mfma_f32_16x16x32_bf16 v[38:41], v[162:165], v[224:227], v[38:41]
	v_mfma_f32_16x16x32_bf16 v[34:37], v[176:179], v[224:227], v[34:37]
	v_mfma_f32_16x16x32_bf16 v[20:23], v[162:165], v[232:235], v[20:23]
	v_mfma_f32_16x16x32_bf16 v[16:19], v[176:179], v[232:235], v[16:19]
	v_mfma_f32_16x16x32_bf16 v[4:7], v[162:165], v[240:243], v[4:7]
	v_mfma_f32_16x16x32_bf16 v[0:3], v[176:179], v[240:243], v[0:3]
	s_setprio 0
	s_barrier
	s_add_u32 s0, s0, 0x100
	s_addc_u32 s1, s1, 0
	s_add_u32 s44, s44, 0x100
	s_addc_u32 s45, s45, 0
	s_cmp_ge_i32 s49, s20
	s_mov_b32 s42, s49
	s_cbranch_scc0 .LBB0_559
	v_readlane_b32 s52, v252, 10
	v_readlane_b32 s53, v252, 11
